# w_o GEMM epilogue hand-written: per-16-row groups with the loads of group j+2 in flight during group j (was 4 serialized load/compute/store batches)
# speedup vs baseline: 1.0055x; 1.0055x over previous
; __device__ __forceinline__ u32x4 pack8(const f32x4 a, const f32x4 b) { u32x4 w; w.x = cvt_pk_bf16(a[0], a[1]); w.y = cvt_pk_bf16(a[2], a[3]); w.z = cvt_pk_bf16(b[0], b[1]); w.w = cvt_pk_bf16(b[2], b[3]); return w; }
;     __device__ __forceinline__ void operator()(const f32x4 (&acc)[2][2][4][2], const pg8::Unit& u, int wr, int wc, int fr, int fq) const {
;         const int row0 = u.pm * 256 + wr * 64 + fr, col0 = u.pn * 256 + wc * 32 + 8 * fq;
; #pragma unroll
;         for (int ai = 0; ai < 2; ++ai)
; #pragma unroll
;             for (int mp = 0; mp < 2; ++mp) {
;                 f32x4 xr[2][2][2]; float iqv[2];
; #pragma unroll
;                 for (int mm = 0; mm < 2; ++mm) { const int row = row0 + ai * 128 + (2 * mp + mm) * 16; iqv[mm] = rs0[row];
; #pragma unroll
;                     for (int bj = 0; bj < 2; ++bj) { const size_t off = (size_t)row * DM + col0 + bj * 128; xr[mm][bj][0] = *(const f32x4*)(x + off); xr[mm][bj][1] = *(const f32x4*)(x + off + 4); } }
; #pragma unroll
;                 for (int mm = 0; mm < 2; ++mm) { const int m = 2 * mp + mm, row = row0 + ai * 128 + m * 16; float ss = 0.f; const float iq = (127.f / QCLIP) * iqv[mm];
; #pragma unroll
;                     for (int bj = 0; bj < 2; ++bj) { const size_t off = (size_t)row * DM + col0 + bj * 128;
;                         const f32x4 h0 = xr[mm][bj][0] + acc[ai][bj][m][0], h1 = xr[mm][bj][1] + acc[ai][bj][m][1];
;                         *(u32x4*)(HB + off) = pack8(h0, h1);
;                         { f32x4 q0, q1;
; #pragma unroll
;                           for (int ee = 0; ee < 4; ++ee) { q0[ee] = fminf(fmaxf(rintf(h0[ee] * iq), -127.f), 127.f); q1[ee] = fminf(fmaxf(rintf(h1[ee] * iq), -127.f), 127.f); }
;                           *(u32x2*)(HQ + off) = pack8_i8(q0, q1); }
;                         ss += (h0[0] * h0[0] + h0[1] * h0[1]) + (h0[2] * h0[2] + h0[3] * h0[3]) + (h1[0] * h1[0] + h1[1] * h1[1]) + (h1[2] * h1[2] + h1[3] * h1[3]); }
.LBB0_1137:
	v_sub_u32_e32 v140, v162, v1
	s_mov_b32 s99, s50
	v_readfirstlane_b32 s98, v140
	s_lshr_b32 s98, s98, 8
	v_lshlrev_b32_e32 v134, 2, v1
	v_lshlrev_b32_e32 v135, 14, v1
	v_lshlrev_b32_e32 v136, 13, v1
	v_lshlrev_b32_e32 v137, 12, v1
	v_lshl_add_u32 v135, v180, 2, v135
	v_lshl_add_u32 v136, v180, 1, v136
	v_add_u32_e32 v137, v137, v180
	v_xor_b32_e32 v138, 16, v184
	v_xor_b32_e32 v139, 32, v184
	v_lshlrev_b32_e32 v138, 2, v138
	v_lshlrev_b32_e32 v139, 2, v139
	s_lshl_b32 s12, s98, 10
	s_add_u32 s14, s36, s12
	s_addc_u32 s15, s37, 0
	s_add_u32 s16, s30, s12
	s_addc_u32 s17, s31, 0
	s_lshl_b32 s12, s98, 22
	s_lshl_b32 s13, s99, 10
	s_add_u32 s12, s12, s13
	s_add_u32 s84, s22, s12
	s_addc_u32 s85, s23, 0
	s_lshr_b32 s13, s12, 1
	s_add_u32 s86, s26, s13
	s_addc_u32 s87, s27, 0
	s_lshr_b32 s13, s12, 2
	s_add_u32 s88, s34, s13
	s_addc_u32 s89, s35, 0
	global_load_dword v162, v134, s[14:15]
	global_load_dwordx4 v[186:189], v135, s[84:85]
	global_load_dwordx4 v[190:193], v135, s[84:85] offset:16
	global_load_dwordx4 v[194:197], v135, s[84:85] offset:512
	global_load_dwordx4 v[198:201], v135, s[84:85] offset:528
	s_add_u32 s84, s84, 0x40000
	s_addc_u32 s85, s85, 0
	global_load_dword v163, v134, s[14:15] offset:64
	global_load_dwordx4 v[202:205], v135, s[84:85]
	global_load_dwordx4 v[206:209], v135, s[84:85] offset:16
	global_load_dwordx4 v[210:213], v135, s[84:85] offset:512
	global_load_dwordx4 v[214:217], v135, s[84:85] offset:528
	s_add_u32 s84, s84, 0x40000
	s_addc_u32 s85, s85, 0
	s_waitcnt vmcnt(5)
	v_mul_f32_e32 v228, 0x41e1c71c, v162
	v_pk_add_f32 v[130:131], v[130:131], v[186:187]
	v_pk_add_f32 v[132:133], v[132:133], v[188:189]
	v_cvt_pk_bf16_f32 v218, v130, v131
	v_cvt_pk_bf16_f32 v219, v132, v133
	v_mul_f32_e32 v164, v228, v130
	v_mul_f32_e32 v165, v228, v131
	v_mul_f32_e32 v166, v228, v132
	v_mul_f32_e32 v167, v228, v133
	v_rndne_f32_e32 v164, v164
	v_rndne_f32_e32 v165, v165
	v_rndne_f32_e32 v166, v166
	v_rndne_f32_e32 v167, v167
	v_med3_f32 v164, v164, s71, v183
	v_med3_f32 v165, v165, s71, v183
	v_med3_f32 v166, v166, s71, v183
	v_med3_f32 v167, v167, s71, v183
	v_cvt_i32_f32_e32 v164, v164
	v_cvt_i32_f32_e32 v165, v165
	v_cvt_i32_f32_e32 v166, v166
	v_cvt_i32_f32_e32 v167, v167
	v_and_b32_e32 v164, 0xff, v164
	v_and_b32_e32 v165, 0xff, v165
	v_and_b32_e32 v166, 0xff, v166
	v_lshl_or_b32 v164, v165, 8, v164
	v_lshl_or_b32 v164, v166, 16, v164
	v_lshl_or_b32 v222, v167, 24, v164
	v_pk_mul_f32 v[224:225], v[130:131], v[130:131]
	v_pk_mul_f32 v[226:227], v[132:133], v[132:133]
	v_pk_add_f32 v[126:127], v[126:127], v[190:191]
	v_pk_add_f32 v[128:129], v[128:129], v[192:193]
	v_cvt_pk_bf16_f32 v220, v126, v127
	v_cvt_pk_bf16_f32 v221, v128, v129
	v_mul_f32_e32 v164, v228, v126
	v_mul_f32_e32 v165, v228, v127
	v_mul_f32_e32 v166, v228, v128
	v_mul_f32_e32 v167, v228, v129
	v_rndne_f32_e32 v164, v164
	v_rndne_f32_e32 v165, v165
	v_rndne_f32_e32 v166, v166
	v_rndne_f32_e32 v167, v167
	v_med3_f32 v164, v164, s71, v183
	v_med3_f32 v165, v165, s71, v183
	v_med3_f32 v166, v166, s71, v183
	v_med3_f32 v167, v167, s71, v183
	v_cvt_i32_f32_e32 v164, v164
	v_cvt_i32_f32_e32 v165, v165
	v_cvt_i32_f32_e32 v166, v166
	v_cvt_i32_f32_e32 v167, v167
	v_and_b32_e32 v164, 0xff, v164
	v_and_b32_e32 v165, 0xff, v165
	v_and_b32_e32 v166, 0xff, v166
	v_lshl_or_b32 v164, v165, 8, v164
	v_lshl_or_b32 v164, v166, 16, v164
	v_lshl_or_b32 v223, v167, 24, v164
	v_pk_fma_f32 v[224:225], v[126:127], v[126:127], v[224:225]
	v_pk_fma_f32 v[226:227], v[128:129], v[128:129], v[226:227]
	global_store_dwordx4 v136, v[218:221], s[86:87]
	global_store_dwordx2 v137, v[222:223], s[88:89]
	s_nop 0
	v_pk_add_f32 v[122:123], v[122:123], v[194:195]
	v_pk_add_f32 v[124:125], v[124:125], v[196:197]
	v_cvt_pk_bf16_f32 v218, v122, v123
	v_cvt_pk_bf16_f32 v219, v124, v125
	v_mul_f32_e32 v164, v228, v122
	v_mul_f32_e32 v165, v228, v123
	v_mul_f32_e32 v166, v228, v124
	v_mul_f32_e32 v167, v228, v125
	v_rndne_f32_e32 v164, v164
	v_rndne_f32_e32 v165, v165
	v_rndne_f32_e32 v166, v166
	v_rndne_f32_e32 v167, v167
	v_med3_f32 v164, v164, s71, v183
	v_med3_f32 v165, v165, s71, v183
	v_med3_f32 v166, v166, s71, v183
	v_med3_f32 v167, v167, s71, v183
	v_cvt_i32_f32_e32 v164, v164
	v_cvt_i32_f32_e32 v165, v165
	v_cvt_i32_f32_e32 v166, v166
	v_cvt_i32_f32_e32 v167, v167
	v_and_b32_e32 v164, 0xff, v164
	v_and_b32_e32 v165, 0xff, v165
	v_and_b32_e32 v166, 0xff, v166
	v_lshl_or_b32 v164, v165, 8, v164
	v_lshl_or_b32 v164, v166, 16, v164
	v_lshl_or_b32 v222, v167, 24, v164
	v_pk_fma_f32 v[224:225], v[122:123], v[122:123], v[224:225]
	v_pk_fma_f32 v[226:227], v[124:125], v[124:125], v[226:227]
	v_pk_add_f32 v[118:119], v[118:119], v[198:199]
	v_pk_add_f32 v[120:121], v[120:121], v[200:201]
	v_cvt_pk_bf16_f32 v220, v118, v119
	v_cvt_pk_bf16_f32 v221, v120, v121
	v_mul_f32_e32 v164, v228, v118
	v_mul_f32_e32 v165, v228, v119
	v_mul_f32_e32 v166, v228, v120
	v_mul_f32_e32 v167, v228, v121
	v_rndne_f32_e32 v164, v164
	v_rndne_f32_e32 v165, v165
	v_rndne_f32_e32 v166, v166
	v_rndne_f32_e32 v167, v167
	v_med3_f32 v164, v164, s71, v183
	v_med3_f32 v165, v165, s71, v183
	v_med3_f32 v166, v166, s71, v183
	v_med3_f32 v167, v167, s71, v183
	v_cvt_i32_f32_e32 v164, v164
	v_cvt_i32_f32_e32 v165, v165
	v_cvt_i32_f32_e32 v166, v166
	v_cvt_i32_f32_e32 v167, v167
	v_and_b32_e32 v164, 0xff, v164
	v_and_b32_e32 v165, 0xff, v165
	v_and_b32_e32 v166, 0xff, v166
	v_lshl_or_b32 v164, v165, 8, v164
	v_lshl_or_b32 v164, v166, 16, v164
	v_lshl_or_b32 v223, v167, 24, v164
	v_pk_fma_f32 v[224:225], v[118:119], v[118:119], v[224:225]
	v_pk_fma_f32 v[226:227], v[120:121], v[120:121], v[226:227]
	global_store_dwordx4 v136, v[218:221], s[86:87] offset:256
	global_store_dwordx2 v137, v[222:223], s[88:89] offset:128
	s_nop 0
	v_add_f32_e32 v224, v224, v225
	v_add_f32_e32 v226, v226, v227
	v_add_f32_e32 v224, v224, v226
	ds_bpermute_b32 v225, v138, v224
	s_waitcnt lgkmcnt(0)
; __device__ __forceinline__ u32x4 pack8(const f32x4 a, const f32x4 b) { u32x4 w; w.x = cvt_pk_bf16(a[0], a[1]); w.y = cvt_pk_bf16(a[2], a[3]); w.z = cvt_pk_bf16(b[0], b[1]); w.w = cvt_pk_bf16(b[2], b[3]); return w; }
;     __device__ __forceinline__ void operator()(const f32x4 (&acc)[2][2][4][2], const pg8::Unit& u, int wr, int wc, int fr, int fq) const {
;     ...
; #pragma unroll
;                 for (int mm = 0; mm < 2; ++mm) { const int m = 2 * mp + mm, row = row0 + ai * 128 + m * 16; float ss = 0.f; const float iq = (127.f / QCLIP) * iqv[mm];
; #pragma unroll
;                     for (int bj = 0; bj < 2; ++bj) { const size_t off = (size_t)row * DM + col0 + bj * 128;
;                         const f32x4 h0 = xr[mm][bj][0] + acc[ai][bj][m][0], h1 = xr[mm][bj][1] + acc[ai][bj][m][1];
;                         *(u32x4*)(HB + off) = pack8(h0, h1);
;                         { f32x4 q0, q1;
; #pragma unroll
;                           for (int ee = 0; ee < 4; ++ee) { q0[ee] = fminf(fmaxf(rintf(h0[ee] * iq), -127.f), 127.f); q1[ee] = fminf(fmaxf(rintf(h1[ee] * iq), -127.f), 127.f); }
;                           *(u32x2*)(HQ + off) = pack8_i8(q0, q1); }
;                         ss += (h0[0] * h0[0] + h0[1] * h0[1]) + (h0[2] * h0[2] + h0[3] * h0[3]) + (h1[0] * h1[0] + h1[1] * h1[1]) + (h1[2] * h1[2] + h1[3] * h1[3]); }
;                     ss += __shfl_xor(ss, 16); ss += __shfl_xor(ss, 32);
;                     if (fq == 0) unsafeAtomicAdd(rss1 + row, ss); }
	v_add_f32_e32 v224, v224, v225
	ds_bpermute_b32 v225, v139, v224
	s_waitcnt lgkmcnt(0)
	v_add_f32_e32 v224, v224, v225
	s_and_saveexec_b64 s[32:33], s[6:7]
	global_atomic_add_f32 v134, v224, s[16:17]
	s_or_b64 exec, exec, s[32:33]
	s_add_u32 s86, s86, 0x20000
	s_addc_u32 s87, s87, 0
	s_add_u32 s88, s88, 0x10000
	s_addc_u32 s89, s89, 0
	global_load_dword v162, v134, s[14:15] offset:128
	global_load_dwordx4 v[186:189], v135, s[84:85]
	global_load_dwordx4 v[190:193], v135, s[84:85] offset:16
	global_load_dwordx4 v[194:197], v135, s[84:85] offset:512
	global_load_dwordx4 v[198:201], v135, s[84:85] offset:528
	s_add_u32 s84, s84, 0x40000
	s_addc_u32 s85, s85, 0
	s_waitcnt vmcnt(10)
	v_mul_f32_e32 v228, 0x41e1c71c, v163
	v_pk_add_f32 v[114:115], v[114:115], v[202:203]
	v_pk_add_f32 v[116:117], v[116:117], v[204:205]
	v_cvt_pk_bf16_f32 v218, v114, v115
	v_cvt_pk_bf16_f32 v219, v116, v117
	v_mul_f32_e32 v164, v228, v114
	v_mul_f32_e32 v165, v228, v115
	v_mul_f32_e32 v166, v228, v116
	v_mul_f32_e32 v167, v228, v117
	v_rndne_f32_e32 v164, v164
	v_rndne_f32_e32 v165, v165
	v_rndne_f32_e32 v166, v166
	v_rndne_f32_e32 v167, v167
	v_med3_f32 v164, v164, s71, v183
	v_med3_f32 v165, v165, s71, v183
	v_med3_f32 v166, v166, s71, v183
	v_med3_f32 v167, v167, s71, v183
	v_cvt_i32_f32_e32 v164, v164
	v_cvt_i32_f32_e32 v165, v165
	v_cvt_i32_f32_e32 v166, v166
	v_cvt_i32_f32_e32 v167, v167
	v_and_b32_e32 v164, 0xff, v164
	v_and_b32_e32 v165, 0xff, v165
	v_and_b32_e32 v166, 0xff, v166
	v_lshl_or_b32 v164, v165, 8, v164
	v_lshl_or_b32 v164, v166, 16, v164
	v_lshl_or_b32 v222, v167, 24, v164
	v_pk_mul_f32 v[224:225], v[114:115], v[114:115]
	v_pk_mul_f32 v[226:227], v[116:117], v[116:117]
	v_pk_add_f32 v[110:111], v[110:111], v[206:207]
	v_pk_add_f32 v[112:113], v[112:113], v[208:209]
	v_cvt_pk_bf16_f32 v220, v110, v111
	v_cvt_pk_bf16_f32 v221, v112, v113
	v_mul_f32_e32 v164, v228, v110
	v_mul_f32_e32 v165, v228, v111
	v_mul_f32_e32 v166, v228, v112
	v_mul_f32_e32 v167, v228, v113
	v_rndne_f32_e32 v164, v164
	v_rndne_f32_e32 v165, v165
	v_rndne_f32_e32 v166, v166
	v_rndne_f32_e32 v167, v167
	v_med3_f32 v164, v164, s71, v183
	v_med3_f32 v165, v165, s71, v183
	v_med3_f32 v166, v166, s71, v183
	v_med3_f32 v167, v167, s71, v183
	v_cvt_i32_f32_e32 v164, v164
	v_cvt_i32_f32_e32 v165, v165
	v_cvt_i32_f32_e32 v166, v166
	v_cvt_i32_f32_e32 v167, v167
	v_and_b32_e32 v164, 0xff, v164
	v_and_b32_e32 v165, 0xff, v165
	v_and_b32_e32 v166, 0xff, v166
	v_lshl_or_b32 v164, v165, 8, v164
	v_lshl_or_b32 v164, v166, 16, v164
	v_lshl_or_b32 v223, v167, 24, v164
	v_pk_fma_f32 v[224:225], v[110:111], v[110:111], v[224:225]
	v_pk_fma_f32 v[226:227], v[112:113], v[112:113], v[226:227]
	global_store_dwordx4 v136, v[218:221], s[86:87]
	global_store_dwordx2 v137, v[222:223], s[88:89]
	s_nop 0
	v_pk_add_f32 v[106:107], v[106:107], v[210:211]
	v_pk_add_f32 v[108:109], v[108:109], v[212:213]
	v_cvt_pk_bf16_f32 v218, v106, v107
	v_cvt_pk_bf16_f32 v219, v108, v109
	v_mul_f32_e32 v164, v228, v106
	v_mul_f32_e32 v165, v228, v107
	v_mul_f32_e32 v166, v228, v108
	v_mul_f32_e32 v167, v228, v109
	v_rndne_f32_e32 v164, v164
	v_rndne_f32_e32 v165, v165
	v_rndne_f32_e32 v166, v166
	v_rndne_f32_e32 v167, v167
	v_med3_f32 v164, v164, s71, v183
	v_med3_f32 v165, v165, s71, v183
	v_med3_f32 v166, v166, s71, v183
	v_med3_f32 v167, v167, s71, v183
	v_cvt_i32_f32_e32 v164, v164
	v_cvt_i32_f32_e32 v165, v165
	v_cvt_i32_f32_e32 v166, v166
	v_cvt_i32_f32_e32 v167, v167
	v_and_b32_e32 v164, 0xff, v164
	v_and_b32_e32 v165, 0xff, v165
	v_and_b32_e32 v166, 0xff, v166
	v_lshl_or_b32 v164, v165, 8, v164
	v_lshl_or_b32 v164, v166, 16, v164
	v_lshl_or_b32 v222, v167, 24, v164
	v_pk_fma_f32 v[224:225], v[106:107], v[106:107], v[224:225]
	v_pk_fma_f32 v[226:227], v[108:109], v[108:109], v[226:227]
	v_pk_add_f32 v[102:103], v[102:103], v[214:215]
	v_pk_add_f32 v[104:105], v[104:105], v[216:217]
	v_cvt_pk_bf16_f32 v220, v102, v103
	v_cvt_pk_bf16_f32 v221, v104, v105
	v_mul_f32_e32 v164, v228, v102
	v_mul_f32_e32 v165, v228, v103
	v_mul_f32_e32 v166, v228, v104
	v_mul_f32_e32 v167, v228, v105
	v_rndne_f32_e32 v164, v164
	v_rndne_f32_e32 v165, v165
	v_rndne_f32_e32 v166, v166
	v_rndne_f32_e32 v167, v167
	v_med3_f32 v164, v164, s71, v183
	v_med3_f32 v165, v165, s71, v183
	v_med3_f32 v166, v166, s71, v183
	v_med3_f32 v167, v167, s71, v183
	v_cvt_i32_f32_e32 v164, v164
	v_cvt_i32_f32_e32 v165, v165
	v_cvt_i32_f32_e32 v166, v166
	v_cvt_i32_f32_e32 v167, v167
	v_and_b32_e32 v164, 0xff, v164
	v_and_b32_e32 v165, 0xff, v165
	v_and_b32_e32 v166, 0xff, v166
	v_lshl_or_b32 v164, v165, 8, v164
	v_lshl_or_b32 v164, v166, 16, v164
	v_lshl_or_b32 v223, v167, 24, v164
	v_pk_fma_f32 v[224:225], v[102:103], v[102:103], v[224:225]
	v_pk_fma_f32 v[226:227], v[104:105], v[104:105], v[226:227]
	global_store_dwordx4 v136, v[218:221], s[86:87] offset:256
	global_store_dwordx2 v137, v[222:223], s[88:89] offset:128
	s_nop 0
	v_add_f32_e32 v224, v224, v225
	v_add_f32_e32 v226, v226, v227
	v_add_f32_e32 v224, v224, v226
	ds_bpermute_b32 v225, v138, v224
	s_waitcnt lgkmcnt(0)
	v_add_f32_e32 v224, v224, v225
	ds_bpermute_b32 v225, v139, v224
	s_waitcnt lgkmcnt(0)
	v_add_f32_e32 v224, v224, v225
	s_and_saveexec_b64 s[32:33], s[6:7]
	global_atomic_add_f32 v134, v224, s[16:17] offset:64
	s_or_b64 exec, exec, s[32:33]
	s_add_u32 s86, s86, 0x20000
	s_addc_u32 s87, s87, 0
	s_add_u32 s88, s88, 0x10000
	s_addc_u32 s89, s89, 0
	global_load_dword v163, v134, s[14:15] offset:192
	global_load_dwordx4 v[202:205], v135, s[84:85]
	global_load_dwordx4 v[206:209], v135, s[84:85] offset:16
	global_load_dwordx4 v[210:213], v135, s[84:85] offset:512
	global_load_dwordx4 v[214:217], v135, s[84:85] offset:528
	s_add_u32 s84, s84, 0x140000
	s_addc_u32 s85, s85, 0
	s_waitcnt vmcnt(10)
; __device__ __forceinline__ u32x4 pack8(const f32x4 a, const f32x4 b) { u32x4 w; w.x = cvt_pk_bf16(a[0], a[1]); w.y = cvt_pk_bf16(a[2], a[3]); w.z = cvt_pk_bf16(b[0], b[1]); w.w = cvt_pk_bf16(b[2], b[3]); return w; }
;     __device__ __forceinline__ void operator()(const f32x4 (&acc)[2][2][4][2], const pg8::Unit& u, int wr, int wc, int fr, int fq) const {
;     ...
; #pragma unroll
;                 for (int mm = 0; mm < 2; ++mm) { const int m = 2 * mp + mm, row = row0 + ai * 128 + m * 16; float ss = 0.f; const float iq = (127.f / QCLIP) * iqv[mm];
; #pragma unroll
;                     for (int bj = 0; bj < 2; ++bj) { const size_t off = (size_t)row * DM + col0 + bj * 128;
;                         const f32x4 h0 = xr[mm][bj][0] + acc[ai][bj][m][0], h1 = xr[mm][bj][1] + acc[ai][bj][m][1];
;                         *(u32x4*)(HB + off) = pack8(h0, h1);
;                         { f32x4 q0, q1;
; #pragma unroll
;                           for (int ee = 0; ee < 4; ++ee) { q0[ee] = fminf(fmaxf(rintf(h0[ee] * iq), -127.f), 127.f); q1[ee] = fminf(fmaxf(rintf(h1[ee] * iq), -127.f), 127.f); }
;                           *(u32x2*)(HQ + off) = pack8_i8(q0, q1); }
;                         ss += (h0[0] * h0[0] + h0[1] * h0[1]) + (h0[2] * h0[2] + h0[3] * h0[3]) + (h1[0] * h1[0] + h1[1] * h1[1]) + (h1[2] * h1[2] + h1[3] * h1[3]); }
;                     ss += __shfl_xor(ss, 16); ss += __shfl_xor(ss, 32);
;                     if (fq == 0) unsafeAtomicAdd(rss1 + row, ss); }
	v_mul_f32_e32 v228, 0x41e1c71c, v162
	v_pk_add_f32 v[98:99], v[98:99], v[186:187]
	v_pk_add_f32 v[100:101], v[100:101], v[188:189]
	v_cvt_pk_bf16_f32 v218, v98, v99
	v_cvt_pk_bf16_f32 v219, v100, v101
	v_mul_f32_e32 v164, v228, v98
	v_mul_f32_e32 v165, v228, v99
	v_mul_f32_e32 v166, v228, v100
	v_mul_f32_e32 v167, v228, v101
	v_rndne_f32_e32 v164, v164
	v_rndne_f32_e32 v165, v165
	v_rndne_f32_e32 v166, v166
	v_rndne_f32_e32 v167, v167
	v_med3_f32 v164, v164, s71, v183
	v_med3_f32 v165, v165, s71, v183
	v_med3_f32 v166, v166, s71, v183
	v_med3_f32 v167, v167, s71, v183
	v_cvt_i32_f32_e32 v164, v164
	v_cvt_i32_f32_e32 v165, v165
	v_cvt_i32_f32_e32 v166, v166
	v_cvt_i32_f32_e32 v167, v167
	v_and_b32_e32 v164, 0xff, v164
	v_and_b32_e32 v165, 0xff, v165
	v_and_b32_e32 v166, 0xff, v166
	v_lshl_or_b32 v164, v165, 8, v164
	v_lshl_or_b32 v164, v166, 16, v164
	v_lshl_or_b32 v222, v167, 24, v164
	v_pk_mul_f32 v[224:225], v[98:99], v[98:99]
	v_pk_mul_f32 v[226:227], v[100:101], v[100:101]
	v_pk_add_f32 v[94:95], v[94:95], v[190:191]
	v_pk_add_f32 v[96:97], v[96:97], v[192:193]
	v_cvt_pk_bf16_f32 v220, v94, v95
	v_cvt_pk_bf16_f32 v221, v96, v97
	v_mul_f32_e32 v164, v228, v94
	v_mul_f32_e32 v165, v228, v95
	v_mul_f32_e32 v166, v228, v96
	v_mul_f32_e32 v167, v228, v97
	v_rndne_f32_e32 v164, v164
	v_rndne_f32_e32 v165, v165
	v_rndne_f32_e32 v166, v166
	v_rndne_f32_e32 v167, v167
	v_med3_f32 v164, v164, s71, v183
	v_med3_f32 v165, v165, s71, v183
	v_med3_f32 v166, v166, s71, v183
	v_med3_f32 v167, v167, s71, v183
	v_cvt_i32_f32_e32 v164, v164
	v_cvt_i32_f32_e32 v165, v165
	v_cvt_i32_f32_e32 v166, v166
	v_cvt_i32_f32_e32 v167, v167
	v_and_b32_e32 v164, 0xff, v164
	v_and_b32_e32 v165, 0xff, v165
	v_and_b32_e32 v166, 0xff, v166
	v_lshl_or_b32 v164, v165, 8, v164
	v_lshl_or_b32 v164, v166, 16, v164
	v_lshl_or_b32 v223, v167, 24, v164
	v_pk_fma_f32 v[224:225], v[94:95], v[94:95], v[224:225]
	v_pk_fma_f32 v[226:227], v[96:97], v[96:97], v[226:227]
	global_store_dwordx4 v136, v[218:221], s[86:87]
	global_store_dwordx2 v137, v[222:223], s[88:89]
	s_nop 0
	v_pk_add_f32 v[90:91], v[90:91], v[194:195]
	v_pk_add_f32 v[92:93], v[92:93], v[196:197]
	v_cvt_pk_bf16_f32 v218, v90, v91
	v_cvt_pk_bf16_f32 v219, v92, v93
	v_mul_f32_e32 v164, v228, v90
	v_mul_f32_e32 v165, v228, v91
	v_mul_f32_e32 v166, v228, v92
	v_mul_f32_e32 v167, v228, v93
	v_rndne_f32_e32 v164, v164
	v_rndne_f32_e32 v165, v165
	v_rndne_f32_e32 v166, v166
	v_rndne_f32_e32 v167, v167
	v_med3_f32 v164, v164, s71, v183
	v_med3_f32 v165, v165, s71, v183
	v_med3_f32 v166, v166, s71, v183
	v_med3_f32 v167, v167, s71, v183
	v_cvt_i32_f32_e32 v164, v164
	v_cvt_i32_f32_e32 v165, v165
	v_cvt_i32_f32_e32 v166, v166
	v_cvt_i32_f32_e32 v167, v167
	v_and_b32_e32 v164, 0xff, v164
	v_and_b32_e32 v165, 0xff, v165
	v_and_b32_e32 v166, 0xff, v166
	v_lshl_or_b32 v164, v165, 8, v164
	v_lshl_or_b32 v164, v166, 16, v164
	v_lshl_or_b32 v222, v167, 24, v164
	v_pk_fma_f32 v[224:225], v[90:91], v[90:91], v[224:225]
	v_pk_fma_f32 v[226:227], v[92:93], v[92:93], v[226:227]
	v_pk_add_f32 v[86:87], v[86:87], v[198:199]
	v_pk_add_f32 v[88:89], v[88:89], v[200:201]
	v_cvt_pk_bf16_f32 v220, v86, v87
	v_cvt_pk_bf16_f32 v221, v88, v89
	v_mul_f32_e32 v164, v228, v86
	v_mul_f32_e32 v165, v228, v87
	v_mul_f32_e32 v166, v228, v88
	v_mul_f32_e32 v167, v228, v89
	v_rndne_f32_e32 v164, v164
	v_rndne_f32_e32 v165, v165
	v_rndne_f32_e32 v166, v166
	v_rndne_f32_e32 v167, v167
	v_med3_f32 v164, v164, s71, v183
	v_med3_f32 v165, v165, s71, v183
	v_med3_f32 v166, v166, s71, v183
	v_med3_f32 v167, v167, s71, v183
	v_cvt_i32_f32_e32 v164, v164
	v_cvt_i32_f32_e32 v165, v165
	v_cvt_i32_f32_e32 v166, v166
	v_cvt_i32_f32_e32 v167, v167
	v_and_b32_e32 v164, 0xff, v164
	v_and_b32_e32 v165, 0xff, v165
	v_and_b32_e32 v166, 0xff, v166
	v_lshl_or_b32 v164, v165, 8, v164
	v_lshl_or_b32 v164, v166, 16, v164
	v_lshl_or_b32 v223, v167, 24, v164
	v_pk_fma_f32 v[224:225], v[86:87], v[86:87], v[224:225]
	v_pk_fma_f32 v[226:227], v[88:89], v[88:89], v[226:227]
	global_store_dwordx4 v136, v[218:221], s[86:87] offset:256
	global_store_dwordx2 v137, v[222:223], s[88:89] offset:128
	s_nop 0
	v_add_f32_e32 v224, v224, v225
	v_add_f32_e32 v226, v226, v227
	v_add_f32_e32 v224, v224, v226
	ds_bpermute_b32 v225, v138, v224
	s_waitcnt lgkmcnt(0)
	v_add_f32_e32 v224, v224, v225
	ds_bpermute_b32 v225, v139, v224
	s_waitcnt lgkmcnt(0)
	v_add_f32_e32 v224, v224, v225
	s_and_saveexec_b64 s[32:33], s[6:7]
	global_atomic_add_f32 v134, v224, s[16:17] offset:128
	s_or_b64 exec, exec, s[32:33]
	s_add_u32 s86, s86, 0x20000
	s_addc_u32 s87, s87, 0
	s_add_u32 s88, s88, 0x10000
	s_addc_u32 s89, s89, 0
	global_load_dword v162, v134, s[14:15] offset:512
	global_load_dwordx4 v[186:189], v135, s[84:85]
	global_load_dwordx4 v[190:193], v135, s[84:85] offset:16
	global_load_dwordx4 v[194:197], v135, s[84:85] offset:512
	global_load_dwordx4 v[198:201], v135, s[84:85] offset:528
	s_add_u32 s84, s84, 0x40000
	s_addc_u32 s85, s85, 0
	s_waitcnt vmcnt(10)
; __device__ __forceinline__ u32x4 pack8(const f32x4 a, const f32x4 b) { u32x4 w; w.x = cvt_pk_bf16(a[0], a[1]); w.y = cvt_pk_bf16(a[2], a[3]); w.z = cvt_pk_bf16(b[0], b[1]); w.w = cvt_pk_bf16(b[2], b[3]); return w; }
;     __device__ __forceinline__ void operator()(const f32x4 (&acc)[2][2][4][2], const pg8::Unit& u, int wr, int wc, int fr, int fq) const {
;     ...
; #pragma unroll
;                 for (int mm = 0; mm < 2; ++mm) { const int m = 2 * mp + mm, row = row0 + ai * 128 + m * 16; float ss = 0.f; const float iq = (127.f / QCLIP) * iqv[mm];
; #pragma unroll
;                     for (int bj = 0; bj < 2; ++bj) { const size_t off = (size_t)row * DM + col0 + bj * 128;
;                         const f32x4 h0 = xr[mm][bj][0] + acc[ai][bj][m][0], h1 = xr[mm][bj][1] + acc[ai][bj][m][1];
;                         *(u32x4*)(HB + off) = pack8(h0, h1);
;                         { f32x4 q0, q1;
; #pragma unroll
;                           for (int ee = 0; ee < 4; ++ee) { q0[ee] = fminf(fmaxf(rintf(h0[ee] * iq), -127.f), 127.f); q1[ee] = fminf(fmaxf(rintf(h1[ee] * iq), -127.f), 127.f); }
;                           *(u32x2*)(HQ + off) = pack8_i8(q0, q1); }
;                         ss += (h0[0] * h0[0] + h0[1] * h0[1]) + (h0[2] * h0[2] + h0[3] * h0[3]) + (h1[0] * h1[0] + h1[1] * h1[1]) + (h1[2] * h1[2] + h1[3] * h1[3]); }
;                     ss += __shfl_xor(ss, 16); ss += __shfl_xor(ss, 32);
;                     if (fq == 0) unsafeAtomicAdd(rss1 + row, ss); }
	v_mul_f32_e32 v228, 0x41e1c71c, v163
	v_pk_add_f32 v[82:83], v[82:83], v[202:203]
	v_pk_add_f32 v[84:85], v[84:85], v[204:205]
	v_cvt_pk_bf16_f32 v218, v82, v83
	v_cvt_pk_bf16_f32 v219, v84, v85
	v_mul_f32_e32 v164, v228, v82
	v_mul_f32_e32 v165, v228, v83
	v_mul_f32_e32 v166, v228, v84
	v_mul_f32_e32 v167, v228, v85
	v_rndne_f32_e32 v164, v164
	v_rndne_f32_e32 v165, v165
	v_rndne_f32_e32 v166, v166
	v_rndne_f32_e32 v167, v167
	v_med3_f32 v164, v164, s71, v183
	v_med3_f32 v165, v165, s71, v183
	v_med3_f32 v166, v166, s71, v183
	v_med3_f32 v167, v167, s71, v183
	v_cvt_i32_f32_e32 v164, v164
	v_cvt_i32_f32_e32 v165, v165
	v_cvt_i32_f32_e32 v166, v166
	v_cvt_i32_f32_e32 v167, v167
	v_and_b32_e32 v164, 0xff, v164
	v_and_b32_e32 v165, 0xff, v165
	v_and_b32_e32 v166, 0xff, v166
	v_lshl_or_b32 v164, v165, 8, v164
	v_lshl_or_b32 v164, v166, 16, v164
	v_lshl_or_b32 v222, v167, 24, v164
	v_pk_mul_f32 v[224:225], v[82:83], v[82:83]
	v_pk_mul_f32 v[226:227], v[84:85], v[84:85]
	v_pk_add_f32 v[78:79], v[78:79], v[206:207]
	v_pk_add_f32 v[80:81], v[80:81], v[208:209]
	v_cvt_pk_bf16_f32 v220, v78, v79
	v_cvt_pk_bf16_f32 v221, v80, v81
	v_mul_f32_e32 v164, v228, v78
	v_mul_f32_e32 v165, v228, v79
	v_mul_f32_e32 v166, v228, v80
	v_mul_f32_e32 v167, v228, v81
	v_rndne_f32_e32 v164, v164
	v_rndne_f32_e32 v165, v165
	v_rndne_f32_e32 v166, v166
	v_rndne_f32_e32 v167, v167
	v_med3_f32 v164, v164, s71, v183
	v_med3_f32 v165, v165, s71, v183
	v_med3_f32 v166, v166, s71, v183
	v_med3_f32 v167, v167, s71, v183
	v_cvt_i32_f32_e32 v164, v164
	v_cvt_i32_f32_e32 v165, v165
	v_cvt_i32_f32_e32 v166, v166
	v_cvt_i32_f32_e32 v167, v167
	v_and_b32_e32 v164, 0xff, v164
	v_and_b32_e32 v165, 0xff, v165
	v_and_b32_e32 v166, 0xff, v166
	v_lshl_or_b32 v164, v165, 8, v164
	v_lshl_or_b32 v164, v166, 16, v164
	v_lshl_or_b32 v223, v167, 24, v164
	v_pk_fma_f32 v[224:225], v[78:79], v[78:79], v[224:225]
	v_pk_fma_f32 v[226:227], v[80:81], v[80:81], v[226:227]
	global_store_dwordx4 v136, v[218:221], s[86:87]
	global_store_dwordx2 v137, v[222:223], s[88:89]
	s_nop 0
	v_pk_add_f32 v[74:75], v[74:75], v[210:211]
	v_pk_add_f32 v[76:77], v[76:77], v[212:213]
	v_cvt_pk_bf16_f32 v218, v74, v75
	v_cvt_pk_bf16_f32 v219, v76, v77
	v_mul_f32_e32 v164, v228, v74
	v_mul_f32_e32 v165, v228, v75
	v_mul_f32_e32 v166, v228, v76
	v_mul_f32_e32 v167, v228, v77
	v_rndne_f32_e32 v164, v164
	v_rndne_f32_e32 v165, v165
	v_rndne_f32_e32 v166, v166
	v_rndne_f32_e32 v167, v167
	v_med3_f32 v164, v164, s71, v183
	v_med3_f32 v165, v165, s71, v183
	v_med3_f32 v166, v166, s71, v183
	v_med3_f32 v167, v167, s71, v183
	v_cvt_i32_f32_e32 v164, v164
	v_cvt_i32_f32_e32 v165, v165
	v_cvt_i32_f32_e32 v166, v166
	v_cvt_i32_f32_e32 v167, v167
	v_and_b32_e32 v164, 0xff, v164
	v_and_b32_e32 v165, 0xff, v165
	v_and_b32_e32 v166, 0xff, v166
	v_lshl_or_b32 v164, v165, 8, v164
	v_lshl_or_b32 v164, v166, 16, v164
	v_lshl_or_b32 v222, v167, 24, v164
	v_pk_fma_f32 v[224:225], v[74:75], v[74:75], v[224:225]
	v_pk_fma_f32 v[226:227], v[76:77], v[76:77], v[226:227]
	v_pk_add_f32 v[70:71], v[70:71], v[214:215]
	v_pk_add_f32 v[72:73], v[72:73], v[216:217]
	v_cvt_pk_bf16_f32 v220, v70, v71
	v_cvt_pk_bf16_f32 v221, v72, v73
	v_mul_f32_e32 v164, v228, v70
	v_mul_f32_e32 v165, v228, v71
	v_mul_f32_e32 v166, v228, v72
	v_mul_f32_e32 v167, v228, v73
	v_rndne_f32_e32 v164, v164
	v_rndne_f32_e32 v165, v165
	v_rndne_f32_e32 v166, v166
	v_rndne_f32_e32 v167, v167
	v_med3_f32 v164, v164, s71, v183
	v_med3_f32 v165, v165, s71, v183
	v_med3_f32 v166, v166, s71, v183
	v_med3_f32 v167, v167, s71, v183
	v_cvt_i32_f32_e32 v164, v164
	v_cvt_i32_f32_e32 v165, v165
	v_cvt_i32_f32_e32 v166, v166
	v_cvt_i32_f32_e32 v167, v167
	v_and_b32_e32 v164, 0xff, v164
	v_and_b32_e32 v165, 0xff, v165
	v_and_b32_e32 v166, 0xff, v166
	v_lshl_or_b32 v164, v165, 8, v164
	v_lshl_or_b32 v164, v166, 16, v164
	v_lshl_or_b32 v223, v167, 24, v164
	v_pk_fma_f32 v[224:225], v[70:71], v[70:71], v[224:225]
	v_pk_fma_f32 v[226:227], v[72:73], v[72:73], v[226:227]
	global_store_dwordx4 v136, v[218:221], s[86:87] offset:256
	global_store_dwordx2 v137, v[222:223], s[88:89] offset:128
	s_nop 0
	v_add_f32_e32 v224, v224, v225
	v_add_f32_e32 v226, v226, v227
	v_add_f32_e32 v224, v224, v226
	ds_bpermute_b32 v225, v138, v224
	s_waitcnt lgkmcnt(0)
	v_add_f32_e32 v224, v224, v225
	ds_bpermute_b32 v225, v139, v224
	s_waitcnt lgkmcnt(0)
	v_add_f32_e32 v224, v224, v225
	s_and_saveexec_b64 s[32:33], s[6:7]
	global_atomic_add_f32 v134, v224, s[16:17] offset:192
	s_or_b64 exec, exec, s[32:33]
	s_add_u32 s86, s86, 0xa0000
	s_addc_u32 s87, s87, 0
	s_add_u32 s88, s88, 0x50000
	s_addc_u32 s89, s89, 0
	global_load_dword v163, v134, s[14:15] offset:576
	global_load_dwordx4 v[202:205], v135, s[84:85]
	global_load_dwordx4 v[206:209], v135, s[84:85] offset:16
	global_load_dwordx4 v[210:213], v135, s[84:85] offset:512
	global_load_dwordx4 v[214:217], v135, s[84:85] offset:528
	s_add_u32 s84, s84, 0x40000
	s_addc_u32 s85, s85, 0
	s_waitcnt vmcnt(10)
; __device__ __forceinline__ u32x4 pack8(const f32x4 a, const f32x4 b) { u32x4 w; w.x = cvt_pk_bf16(a[0], a[1]); w.y = cvt_pk_bf16(a[2], a[3]); w.z = cvt_pk_bf16(b[0], b[1]); w.w = cvt_pk_bf16(b[2], b[3]); return w; }
;     __device__ __forceinline__ void operator()(const f32x4 (&acc)[2][2][4][2], const pg8::Unit& u, int wr, int wc, int fr, int fq) const {
;     ...
; #pragma unroll
;                 for (int mm = 0; mm < 2; ++mm) { const int m = 2 * mp + mm, row = row0 + ai * 128 + m * 16; float ss = 0.f; const float iq = (127.f / QCLIP) * iqv[mm];
; #pragma unroll
;                     for (int bj = 0; bj < 2; ++bj) { const size_t off = (size_t)row * DM + col0 + bj * 128;
;                         const f32x4 h0 = xr[mm][bj][0] + acc[ai][bj][m][0], h1 = xr[mm][bj][1] + acc[ai][bj][m][1];
;                         *(u32x4*)(HB + off) = pack8(h0, h1);
;                         { f32x4 q0, q1;
; #pragma unroll
;                           for (int ee = 0; ee < 4; ++ee) { q0[ee] = fminf(fmaxf(rintf(h0[ee] * iq), -127.f), 127.f); q1[ee] = fminf(fmaxf(rintf(h1[ee] * iq), -127.f), 127.f); }
;                           *(u32x2*)(HQ + off) = pack8_i8(q0, q1); }
;                         ss += (h0[0] * h0[0] + h0[1] * h0[1]) + (h0[2] * h0[2] + h0[3] * h0[3]) + (h1[0] * h1[0] + h1[1] * h1[1]) + (h1[2] * h1[2] + h1[3] * h1[3]); }
;                     ss += __shfl_xor(ss, 16); ss += __shfl_xor(ss, 32);
;                     if (fq == 0) unsafeAtomicAdd(rss1 + row, ss); }
	v_mul_f32_e32 v228, 0x41e1c71c, v162
	v_pk_add_f32 v[66:67], v[66:67], v[186:187]
	v_pk_add_f32 v[68:69], v[68:69], v[188:189]
	v_cvt_pk_bf16_f32 v218, v66, v67
	v_cvt_pk_bf16_f32 v219, v68, v69
	v_mul_f32_e32 v164, v228, v66
	v_mul_f32_e32 v165, v228, v67
	v_mul_f32_e32 v166, v228, v68
	v_mul_f32_e32 v167, v228, v69
	v_rndne_f32_e32 v164, v164
	v_rndne_f32_e32 v165, v165
	v_rndne_f32_e32 v166, v166
	v_rndne_f32_e32 v167, v167
	v_med3_f32 v164, v164, s71, v183
	v_med3_f32 v165, v165, s71, v183
	v_med3_f32 v166, v166, s71, v183
	v_med3_f32 v167, v167, s71, v183
	v_cvt_i32_f32_e32 v164, v164
	v_cvt_i32_f32_e32 v165, v165
	v_cvt_i32_f32_e32 v166, v166
	v_cvt_i32_f32_e32 v167, v167
	v_and_b32_e32 v164, 0xff, v164
	v_and_b32_e32 v165, 0xff, v165
	v_and_b32_e32 v166, 0xff, v166
	v_lshl_or_b32 v164, v165, 8, v164
	v_lshl_or_b32 v164, v166, 16, v164
	v_lshl_or_b32 v222, v167, 24, v164
	v_pk_mul_f32 v[224:225], v[66:67], v[66:67]
	v_pk_mul_f32 v[226:227], v[68:69], v[68:69]
	v_pk_add_f32 v[62:63], v[62:63], v[190:191]
	v_pk_add_f32 v[64:65], v[64:65], v[192:193]
	v_cvt_pk_bf16_f32 v220, v62, v63
	v_cvt_pk_bf16_f32 v221, v64, v65
	v_mul_f32_e32 v164, v228, v62
	v_mul_f32_e32 v165, v228, v63
	v_mul_f32_e32 v166, v228, v64
	v_mul_f32_e32 v167, v228, v65
	v_rndne_f32_e32 v164, v164
	v_rndne_f32_e32 v165, v165
	v_rndne_f32_e32 v166, v166
	v_rndne_f32_e32 v167, v167
	v_med3_f32 v164, v164, s71, v183
	v_med3_f32 v165, v165, s71, v183
	v_med3_f32 v166, v166, s71, v183
	v_med3_f32 v167, v167, s71, v183
	v_cvt_i32_f32_e32 v164, v164
	v_cvt_i32_f32_e32 v165, v165
	v_cvt_i32_f32_e32 v166, v166
	v_cvt_i32_f32_e32 v167, v167
	v_and_b32_e32 v164, 0xff, v164
	v_and_b32_e32 v165, 0xff, v165
	v_and_b32_e32 v166, 0xff, v166
	v_lshl_or_b32 v164, v165, 8, v164
	v_lshl_or_b32 v164, v166, 16, v164
	v_lshl_or_b32 v223, v167, 24, v164
	v_pk_fma_f32 v[224:225], v[62:63], v[62:63], v[224:225]
	v_pk_fma_f32 v[226:227], v[64:65], v[64:65], v[226:227]
	global_store_dwordx4 v136, v[218:221], s[86:87]
	global_store_dwordx2 v137, v[222:223], s[88:89]
	s_nop 0
	v_pk_add_f32 v[58:59], v[58:59], v[194:195]
	v_pk_add_f32 v[60:61], v[60:61], v[196:197]
	v_cvt_pk_bf16_f32 v218, v58, v59
	v_cvt_pk_bf16_f32 v219, v60, v61
	v_mul_f32_e32 v164, v228, v58
	v_mul_f32_e32 v165, v228, v59
	v_mul_f32_e32 v166, v228, v60
	v_mul_f32_e32 v167, v228, v61
	v_rndne_f32_e32 v164, v164
	v_rndne_f32_e32 v165, v165
	v_rndne_f32_e32 v166, v166
	v_rndne_f32_e32 v167, v167
	v_med3_f32 v164, v164, s71, v183
	v_med3_f32 v165, v165, s71, v183
	v_med3_f32 v166, v166, s71, v183
	v_med3_f32 v167, v167, s71, v183
	v_cvt_i32_f32_e32 v164, v164
	v_cvt_i32_f32_e32 v165, v165
	v_cvt_i32_f32_e32 v166, v166
	v_cvt_i32_f32_e32 v167, v167
	v_and_b32_e32 v164, 0xff, v164
	v_and_b32_e32 v165, 0xff, v165
	v_and_b32_e32 v166, 0xff, v166
	v_lshl_or_b32 v164, v165, 8, v164
	v_lshl_or_b32 v164, v166, 16, v164
	v_lshl_or_b32 v222, v167, 24, v164
	v_pk_fma_f32 v[224:225], v[58:59], v[58:59], v[224:225]
	v_pk_fma_f32 v[226:227], v[60:61], v[60:61], v[226:227]
	v_pk_add_f32 v[54:55], v[54:55], v[198:199]
	v_pk_add_f32 v[56:57], v[56:57], v[200:201]
	v_cvt_pk_bf16_f32 v220, v54, v55
	v_cvt_pk_bf16_f32 v221, v56, v57
	v_mul_f32_e32 v164, v228, v54
	v_mul_f32_e32 v165, v228, v55
	v_mul_f32_e32 v166, v228, v56
	v_mul_f32_e32 v167, v228, v57
	v_rndne_f32_e32 v164, v164
	v_rndne_f32_e32 v165, v165
	v_rndne_f32_e32 v166, v166
	v_rndne_f32_e32 v167, v167
	v_med3_f32 v164, v164, s71, v183
	v_med3_f32 v165, v165, s71, v183
	v_med3_f32 v166, v166, s71, v183
	v_med3_f32 v167, v167, s71, v183
	v_cvt_i32_f32_e32 v164, v164
	v_cvt_i32_f32_e32 v165, v165
	v_cvt_i32_f32_e32 v166, v166
	v_cvt_i32_f32_e32 v167, v167
	v_and_b32_e32 v164, 0xff, v164
	v_and_b32_e32 v165, 0xff, v165
	v_and_b32_e32 v166, 0xff, v166
	v_lshl_or_b32 v164, v165, 8, v164
	v_lshl_or_b32 v164, v166, 16, v164
	v_lshl_or_b32 v223, v167, 24, v164
	v_pk_fma_f32 v[224:225], v[54:55], v[54:55], v[224:225]
	v_pk_fma_f32 v[226:227], v[56:57], v[56:57], v[226:227]
	global_store_dwordx4 v136, v[218:221], s[86:87] offset:256
	global_store_dwordx2 v137, v[222:223], s[88:89] offset:128
	s_nop 0
	v_add_f32_e32 v224, v224, v225
	v_add_f32_e32 v226, v226, v227
	v_add_f32_e32 v224, v224, v226
	ds_bpermute_b32 v225, v138, v224
	s_waitcnt lgkmcnt(0)
	v_add_f32_e32 v224, v224, v225
	ds_bpermute_b32 v225, v139, v224
	s_waitcnt lgkmcnt(0)
	v_add_f32_e32 v224, v224, v225
	s_and_saveexec_b64 s[32:33], s[6:7]
	global_atomic_add_f32 v134, v224, s[16:17] offset:512
	s_or_b64 exec, exec, s[32:33]
	s_add_u32 s86, s86, 0x20000
	s_addc_u32 s87, s87, 0
	s_add_u32 s88, s88, 0x10000
	s_addc_u32 s89, s89, 0
	global_load_dword v162, v134, s[14:15] offset:640
	global_load_dwordx4 v[186:189], v135, s[84:85]
	global_load_dwordx4 v[190:193], v135, s[84:85] offset:16
	global_load_dwordx4 v[194:197], v135, s[84:85] offset:512
	global_load_dwordx4 v[198:201], v135, s[84:85] offset:528
	s_add_u32 s84, s84, 0x40000
	s_addc_u32 s85, s85, 0
	s_waitcnt vmcnt(10)
; __device__ __forceinline__ u32x4 pack8(const f32x4 a, const f32x4 b) { u32x4 w; w.x = cvt_pk_bf16(a[0], a[1]); w.y = cvt_pk_bf16(a[2], a[3]); w.z = cvt_pk_bf16(b[0], b[1]); w.w = cvt_pk_bf16(b[2], b[3]); return w; }
;     __device__ __forceinline__ void operator()(const f32x4 (&acc)[2][2][4][2], const pg8::Unit& u, int wr, int wc, int fr, int fq) const {
;     ...
; #pragma unroll
;                 for (int mm = 0; mm < 2; ++mm) { const int m = 2 * mp + mm, row = row0 + ai * 128 + m * 16; float ss = 0.f; const float iq = (127.f / QCLIP) * iqv[mm];
; #pragma unroll
;                     for (int bj = 0; bj < 2; ++bj) { const size_t off = (size_t)row * DM + col0 + bj * 128;
;                         const f32x4 h0 = xr[mm][bj][0] + acc[ai][bj][m][0], h1 = xr[mm][bj][1] + acc[ai][bj][m][1];
;                         *(u32x4*)(HB + off) = pack8(h0, h1);
;                         { f32x4 q0, q1;
; #pragma unroll
;                           for (int ee = 0; ee < 4; ++ee) { q0[ee] = fminf(fmaxf(rintf(h0[ee] * iq), -127.f), 127.f); q1[ee] = fminf(fmaxf(rintf(h1[ee] * iq), -127.f), 127.f); }
;                           *(u32x2*)(HQ + off) = pack8_i8(q0, q1); }
;                         ss += (h0[0] * h0[0] + h0[1] * h0[1]) + (h0[2] * h0[2] + h0[3] * h0[3]) + (h1[0] * h1[0] + h1[1] * h1[1]) + (h1[2] * h1[2] + h1[3] * h1[3]); }
;                     ss += __shfl_xor(ss, 16); ss += __shfl_xor(ss, 32);
;                     if (fq == 0) unsafeAtomicAdd(rss1 + row, ss); }
	v_mul_f32_e32 v228, 0x41e1c71c, v163
	v_pk_add_f32 v[50:51], v[50:51], v[202:203]
	v_pk_add_f32 v[52:53], v[52:53], v[204:205]
	v_cvt_pk_bf16_f32 v218, v50, v51
	v_cvt_pk_bf16_f32 v219, v52, v53
	v_mul_f32_e32 v164, v228, v50
	v_mul_f32_e32 v165, v228, v51
	v_mul_f32_e32 v166, v228, v52
	v_mul_f32_e32 v167, v228, v53
	v_rndne_f32_e32 v164, v164
	v_rndne_f32_e32 v165, v165
	v_rndne_f32_e32 v166, v166
	v_rndne_f32_e32 v167, v167
	v_med3_f32 v164, v164, s71, v183
	v_med3_f32 v165, v165, s71, v183
	v_med3_f32 v166, v166, s71, v183
	v_med3_f32 v167, v167, s71, v183
	v_cvt_i32_f32_e32 v164, v164
	v_cvt_i32_f32_e32 v165, v165
	v_cvt_i32_f32_e32 v166, v166
	v_cvt_i32_f32_e32 v167, v167
	v_and_b32_e32 v164, 0xff, v164
	v_and_b32_e32 v165, 0xff, v165
	v_and_b32_e32 v166, 0xff, v166
	v_lshl_or_b32 v164, v165, 8, v164
	v_lshl_or_b32 v164, v166, 16, v164
	v_lshl_or_b32 v222, v167, 24, v164
	v_pk_mul_f32 v[224:225], v[50:51], v[50:51]
	v_pk_mul_f32 v[226:227], v[52:53], v[52:53]
	v_pk_add_f32 v[46:47], v[46:47], v[206:207]
	v_pk_add_f32 v[48:49], v[48:49], v[208:209]
	v_cvt_pk_bf16_f32 v220, v46, v47
	v_cvt_pk_bf16_f32 v221, v48, v49
	v_mul_f32_e32 v164, v228, v46
	v_mul_f32_e32 v165, v228, v47
	v_mul_f32_e32 v166, v228, v48
	v_mul_f32_e32 v167, v228, v49
	v_rndne_f32_e32 v164, v164
	v_rndne_f32_e32 v165, v165
	v_rndne_f32_e32 v166, v166
	v_rndne_f32_e32 v167, v167
	v_med3_f32 v164, v164, s71, v183
	v_med3_f32 v165, v165, s71, v183
	v_med3_f32 v166, v166, s71, v183
	v_med3_f32 v167, v167, s71, v183
	v_cvt_i32_f32_e32 v164, v164
	v_cvt_i32_f32_e32 v165, v165
	v_cvt_i32_f32_e32 v166, v166
	v_cvt_i32_f32_e32 v167, v167
	v_and_b32_e32 v164, 0xff, v164
	v_and_b32_e32 v165, 0xff, v165
	v_and_b32_e32 v166, 0xff, v166
	v_lshl_or_b32 v164, v165, 8, v164
	v_lshl_or_b32 v164, v166, 16, v164
	v_lshl_or_b32 v223, v167, 24, v164
	v_pk_fma_f32 v[224:225], v[46:47], v[46:47], v[224:225]
	v_pk_fma_f32 v[226:227], v[48:49], v[48:49], v[226:227]
	global_store_dwordx4 v136, v[218:221], s[86:87]
	global_store_dwordx2 v137, v[222:223], s[88:89]
	s_nop 0
	v_pk_add_f32 v[42:43], v[42:43], v[210:211]
	v_pk_add_f32 v[44:45], v[44:45], v[212:213]
	v_cvt_pk_bf16_f32 v218, v42, v43
	v_cvt_pk_bf16_f32 v219, v44, v45
	v_mul_f32_e32 v164, v228, v42
	v_mul_f32_e32 v165, v228, v43
	v_mul_f32_e32 v166, v228, v44
	v_mul_f32_e32 v167, v228, v45
	v_rndne_f32_e32 v164, v164
	v_rndne_f32_e32 v165, v165
	v_rndne_f32_e32 v166, v166
	v_rndne_f32_e32 v167, v167
	v_med3_f32 v164, v164, s71, v183
	v_med3_f32 v165, v165, s71, v183
	v_med3_f32 v166, v166, s71, v183
	v_med3_f32 v167, v167, s71, v183
	v_cvt_i32_f32_e32 v164, v164
	v_cvt_i32_f32_e32 v165, v165
	v_cvt_i32_f32_e32 v166, v166
	v_cvt_i32_f32_e32 v167, v167
	v_and_b32_e32 v164, 0xff, v164
	v_and_b32_e32 v165, 0xff, v165
	v_and_b32_e32 v166, 0xff, v166
	v_lshl_or_b32 v164, v165, 8, v164
	v_lshl_or_b32 v164, v166, 16, v164
	v_lshl_or_b32 v222, v167, 24, v164
	v_pk_fma_f32 v[224:225], v[42:43], v[42:43], v[224:225]
	v_pk_fma_f32 v[226:227], v[44:45], v[44:45], v[226:227]
	v_pk_add_f32 v[38:39], v[38:39], v[214:215]
	v_pk_add_f32 v[40:41], v[40:41], v[216:217]
	v_cvt_pk_bf16_f32 v220, v38, v39
	v_cvt_pk_bf16_f32 v221, v40, v41
	v_mul_f32_e32 v164, v228, v38
	v_mul_f32_e32 v165, v228, v39
	v_mul_f32_e32 v166, v228, v40
	v_mul_f32_e32 v167, v228, v41
	v_rndne_f32_e32 v164, v164
	v_rndne_f32_e32 v165, v165
	v_rndne_f32_e32 v166, v166
	v_rndne_f32_e32 v167, v167
	v_med3_f32 v164, v164, s71, v183
	v_med3_f32 v165, v165, s71, v183
	v_med3_f32 v166, v166, s71, v183
	v_med3_f32 v167, v167, s71, v183
	v_cvt_i32_f32_e32 v164, v164
	v_cvt_i32_f32_e32 v165, v165
	v_cvt_i32_f32_e32 v166, v166
	v_cvt_i32_f32_e32 v167, v167
	v_and_b32_e32 v164, 0xff, v164
	v_and_b32_e32 v165, 0xff, v165
	v_and_b32_e32 v166, 0xff, v166
	v_lshl_or_b32 v164, v165, 8, v164
	v_lshl_or_b32 v164, v166, 16, v164
	v_lshl_or_b32 v223, v167, 24, v164
	v_pk_fma_f32 v[224:225], v[38:39], v[38:39], v[224:225]
	v_pk_fma_f32 v[226:227], v[40:41], v[40:41], v[226:227]
	global_store_dwordx4 v136, v[218:221], s[86:87] offset:256
	global_store_dwordx2 v137, v[222:223], s[88:89] offset:128
	s_nop 0
	v_add_f32_e32 v224, v224, v225
	v_add_f32_e32 v226, v226, v227
	v_add_f32_e32 v224, v224, v226
	ds_bpermute_b32 v225, v138, v224
	s_waitcnt lgkmcnt(0)
	v_add_f32_e32 v224, v224, v225
	ds_bpermute_b32 v225, v139, v224
	s_waitcnt lgkmcnt(0)
	v_add_f32_e32 v224, v224, v225
	s_and_saveexec_b64 s[32:33], s[6:7]
	global_atomic_add_f32 v134, v224, s[16:17] offset:576
	s_or_b64 exec, exec, s[32:33]
	s_add_u32 s86, s86, 0x20000
	s_addc_u32 s87, s87, 0
	s_add_u32 s88, s88, 0x10000
	s_addc_u32 s89, s89, 0
	global_load_dword v163, v134, s[14:15] offset:704
	global_load_dwordx4 v[202:205], v135, s[84:85]
	global_load_dwordx4 v[206:209], v135, s[84:85] offset:16
	global_load_dwordx4 v[210:213], v135, s[84:85] offset:512
	global_load_dwordx4 v[214:217], v135, s[84:85] offset:528
	s_waitcnt vmcnt(10)
; __device__ __forceinline__ u32x4 pack8(const f32x4 a, const f32x4 b) { u32x4 w; w.x = cvt_pk_bf16(a[0], a[1]); w.y = cvt_pk_bf16(a[2], a[3]); w.z = cvt_pk_bf16(b[0], b[1]); w.w = cvt_pk_bf16(b[2], b[3]); return w; }
;     __device__ __forceinline__ void operator()(const f32x4 (&acc)[2][2][4][2], const pg8::Unit& u, int wr, int wc, int fr, int fq) const {
;     ...
; #pragma unroll
;                 for (int mm = 0; mm < 2; ++mm) { const int m = 2 * mp + mm, row = row0 + ai * 128 + m * 16; float ss = 0.f; const float iq = (127.f / QCLIP) * iqv[mm];
; #pragma unroll
;                     for (int bj = 0; bj < 2; ++bj) { const size_t off = (size_t)row * DM + col0 + bj * 128;
;                         const f32x4 h0 = xr[mm][bj][0] + acc[ai][bj][m][0], h1 = xr[mm][bj][1] + acc[ai][bj][m][1];
;                         *(u32x4*)(HB + off) = pack8(h0, h1);
;                         { f32x4 q0, q1;
; #pragma unroll
;                           for (int ee = 0; ee < 4; ++ee) { q0[ee] = fminf(fmaxf(rintf(h0[ee] * iq), -127.f), 127.f); q1[ee] = fminf(fmaxf(rintf(h1[ee] * iq), -127.f), 127.f); }
;                           *(u32x2*)(HQ + off) = pack8_i8(q0, q1); }
;                         ss += (h0[0] * h0[0] + h0[1] * h0[1]) + (h0[2] * h0[2] + h0[3] * h0[3]) + (h1[0] * h1[0] + h1[1] * h1[1]) + (h1[2] * h1[2] + h1[3] * h1[3]); }
;                     ss += __shfl_xor(ss, 16); ss += __shfl_xor(ss, 32);
;                     if (fq == 0) unsafeAtomicAdd(rss1 + row, ss); }
	v_mul_f32_e32 v228, 0x41e1c71c, v162
	v_pk_add_f32 v[34:35], v[34:35], v[186:187]
	v_pk_add_f32 v[36:37], v[36:37], v[188:189]
	v_cvt_pk_bf16_f32 v218, v34, v35
	v_cvt_pk_bf16_f32 v219, v36, v37
	v_mul_f32_e32 v164, v228, v34
	v_mul_f32_e32 v165, v228, v35
	v_mul_f32_e32 v166, v228, v36
	v_mul_f32_e32 v167, v228, v37
	v_rndne_f32_e32 v164, v164
	v_rndne_f32_e32 v165, v165
	v_rndne_f32_e32 v166, v166
	v_rndne_f32_e32 v167, v167
	v_med3_f32 v164, v164, s71, v183
	v_med3_f32 v165, v165, s71, v183
	v_med3_f32 v166, v166, s71, v183
	v_med3_f32 v167, v167, s71, v183
	v_cvt_i32_f32_e32 v164, v164
	v_cvt_i32_f32_e32 v165, v165
	v_cvt_i32_f32_e32 v166, v166
	v_cvt_i32_f32_e32 v167, v167
	v_and_b32_e32 v164, 0xff, v164
	v_and_b32_e32 v165, 0xff, v165
	v_and_b32_e32 v166, 0xff, v166
	v_lshl_or_b32 v164, v165, 8, v164
	v_lshl_or_b32 v164, v166, 16, v164
	v_lshl_or_b32 v222, v167, 24, v164
	v_pk_mul_f32 v[224:225], v[34:35], v[34:35]
	v_pk_mul_f32 v[226:227], v[36:37], v[36:37]
	v_pk_add_f32 v[30:31], v[30:31], v[190:191]
	v_pk_add_f32 v[32:33], v[32:33], v[192:193]
	v_cvt_pk_bf16_f32 v220, v30, v31
	v_cvt_pk_bf16_f32 v221, v32, v33
	v_mul_f32_e32 v164, v228, v30
	v_mul_f32_e32 v165, v228, v31
	v_mul_f32_e32 v166, v228, v32
	v_mul_f32_e32 v167, v228, v33
	v_rndne_f32_e32 v164, v164
	v_rndne_f32_e32 v165, v165
	v_rndne_f32_e32 v166, v166
	v_rndne_f32_e32 v167, v167
	v_med3_f32 v164, v164, s71, v183
	v_med3_f32 v165, v165, s71, v183
	v_med3_f32 v166, v166, s71, v183
	v_med3_f32 v167, v167, s71, v183
	v_cvt_i32_f32_e32 v164, v164
	v_cvt_i32_f32_e32 v165, v165
	v_cvt_i32_f32_e32 v166, v166
	v_cvt_i32_f32_e32 v167, v167
	v_and_b32_e32 v164, 0xff, v164
	v_and_b32_e32 v165, 0xff, v165
	v_and_b32_e32 v166, 0xff, v166
	v_lshl_or_b32 v164, v165, 8, v164
	v_lshl_or_b32 v164, v166, 16, v164
	v_lshl_or_b32 v223, v167, 24, v164
	v_pk_fma_f32 v[224:225], v[30:31], v[30:31], v[224:225]
	v_pk_fma_f32 v[226:227], v[32:33], v[32:33], v[226:227]
	global_store_dwordx4 v136, v[218:221], s[86:87]
	global_store_dwordx2 v137, v[222:223], s[88:89]
	s_nop 0
	v_pk_add_f32 v[26:27], v[26:27], v[194:195]
	v_pk_add_f32 v[28:29], v[28:29], v[196:197]
	v_cvt_pk_bf16_f32 v218, v26, v27
	v_cvt_pk_bf16_f32 v219, v28, v29
	v_mul_f32_e32 v164, v228, v26
	v_mul_f32_e32 v165, v228, v27
	v_mul_f32_e32 v166, v228, v28
	v_mul_f32_e32 v167, v228, v29
	v_rndne_f32_e32 v164, v164
	v_rndne_f32_e32 v165, v165
	v_rndne_f32_e32 v166, v166
	v_rndne_f32_e32 v167, v167
	v_med3_f32 v164, v164, s71, v183
	v_med3_f32 v165, v165, s71, v183
	v_med3_f32 v166, v166, s71, v183
	v_med3_f32 v167, v167, s71, v183
	v_cvt_i32_f32_e32 v164, v164
	v_cvt_i32_f32_e32 v165, v165
	v_cvt_i32_f32_e32 v166, v166
	v_cvt_i32_f32_e32 v167, v167
	v_and_b32_e32 v164, 0xff, v164
	v_and_b32_e32 v165, 0xff, v165
	v_and_b32_e32 v166, 0xff, v166
	v_lshl_or_b32 v164, v165, 8, v164
	v_lshl_or_b32 v164, v166, 16, v164
	v_lshl_or_b32 v222, v167, 24, v164
	v_pk_fma_f32 v[224:225], v[26:27], v[26:27], v[224:225]
	v_pk_fma_f32 v[226:227], v[28:29], v[28:29], v[226:227]
	v_pk_add_f32 v[22:23], v[22:23], v[198:199]
	v_pk_add_f32 v[24:25], v[24:25], v[200:201]
	v_cvt_pk_bf16_f32 v220, v22, v23
	v_cvt_pk_bf16_f32 v221, v24, v25
	v_mul_f32_e32 v164, v228, v22
	v_mul_f32_e32 v165, v228, v23
	v_mul_f32_e32 v166, v228, v24
	v_mul_f32_e32 v167, v228, v25
	v_rndne_f32_e32 v164, v164
	v_rndne_f32_e32 v165, v165
	v_rndne_f32_e32 v166, v166
	v_rndne_f32_e32 v167, v167
	v_med3_f32 v164, v164, s71, v183
	v_med3_f32 v165, v165, s71, v183
	v_med3_f32 v166, v166, s71, v183
	v_med3_f32 v167, v167, s71, v183
	v_cvt_i32_f32_e32 v164, v164
	v_cvt_i32_f32_e32 v165, v165
	v_cvt_i32_f32_e32 v166, v166
	v_cvt_i32_f32_e32 v167, v167
	v_and_b32_e32 v164, 0xff, v164
	v_and_b32_e32 v165, 0xff, v165
	v_and_b32_e32 v166, 0xff, v166
	v_lshl_or_b32 v164, v165, 8, v164
	v_lshl_or_b32 v164, v166, 16, v164
	v_lshl_or_b32 v223, v167, 24, v164
	v_pk_fma_f32 v[224:225], v[22:23], v[22:23], v[224:225]
	v_pk_fma_f32 v[226:227], v[24:25], v[24:25], v[226:227]
	global_store_dwordx4 v136, v[218:221], s[86:87] offset:256
	global_store_dwordx2 v137, v[222:223], s[88:89] offset:128
	s_nop 0
	v_add_f32_e32 v224, v224, v225
	v_add_f32_e32 v226, v226, v227
	v_add_f32_e32 v224, v224, v226
	ds_bpermute_b32 v225, v138, v224
	s_waitcnt lgkmcnt(0)
	v_add_f32_e32 v224, v224, v225
	ds_bpermute_b32 v225, v139, v224
	s_waitcnt lgkmcnt(0)
	v_add_f32_e32 v224, v224, v225
	s_and_saveexec_b64 s[32:33], s[6:7]
	global_atomic_add_f32 v134, v224, s[16:17] offset:640
	s_or_b64 exec, exec, s[32:33]
	s_add_u32 s86, s86, 0x20000
	s_addc_u32 s87, s87, 0
	s_add_u32 s88, s88, 0x10000
	s_addc_u32 s89, s89, 0
	s_waitcnt vmcnt(5)
; __device__ __forceinline__ u32x4 pack8(const f32x4 a, const f32x4 b) { u32x4 w; w.x = cvt_pk_bf16(a[0], a[1]); w.y = cvt_pk_bf16(a[2], a[3]); w.z = cvt_pk_bf16(b[0], b[1]); w.w = cvt_pk_bf16(b[2], b[3]); return w; }
;     __device__ __forceinline__ void operator()(const f32x4 (&acc)[2][2][4][2], const pg8::Unit& u, int wr, int wc, int fr, int fq) const {
;     ...
; #pragma unroll
;                 for (int mm = 0; mm < 2; ++mm) { const int m = 2 * mp + mm, row = row0 + ai * 128 + m * 16; float ss = 0.f; const float iq = (127.f / QCLIP) * iqv[mm];
; #pragma unroll
;                     for (int bj = 0; bj < 2; ++bj) { const size_t off = (size_t)row * DM + col0 + bj * 128;
;                         const f32x4 h0 = xr[mm][bj][0] + acc[ai][bj][m][0], h1 = xr[mm][bj][1] + acc[ai][bj][m][1];
;                         *(u32x4*)(HB + off) = pack8(h0, h1);
;                         { f32x4 q0, q1;
; #pragma unroll
;                           for (int ee = 0; ee < 4; ++ee) { q0[ee] = fminf(fmaxf(rintf(h0[ee] * iq), -127.f), 127.f); q1[ee] = fminf(fmaxf(rintf(h1[ee] * iq), -127.f), 127.f); }
;                           *(u32x2*)(HQ + off) = pack8_i8(q0, q1); }
;                         ss += (h0[0] * h0[0] + h0[1] * h0[1]) + (h0[2] * h0[2] + h0[3] * h0[3]) + (h1[0] * h1[0] + h1[1] * h1[1]) + (h1[2] * h1[2] + h1[3] * h1[3]); }
;                     ss += __shfl_xor(ss, 16); ss += __shfl_xor(ss, 32);
;                     if (fq == 0) unsafeAtomicAdd(rss1 + row, ss); }
	v_mul_f32_e32 v228, 0x41e1c71c, v163
	v_pk_add_f32 v[18:19], v[18:19], v[202:203]
	v_pk_add_f32 v[20:21], v[20:21], v[204:205]
	v_cvt_pk_bf16_f32 v218, v18, v19
	v_cvt_pk_bf16_f32 v219, v20, v21
	v_mul_f32_e32 v164, v228, v18
	v_mul_f32_e32 v165, v228, v19
	v_mul_f32_e32 v166, v228, v20
	v_mul_f32_e32 v167, v228, v21
	v_rndne_f32_e32 v164, v164
	v_rndne_f32_e32 v165, v165
	v_rndne_f32_e32 v166, v166
	v_rndne_f32_e32 v167, v167
	v_med3_f32 v164, v164, s71, v183
	v_med3_f32 v165, v165, s71, v183
	v_med3_f32 v166, v166, s71, v183
	v_med3_f32 v167, v167, s71, v183
	v_cvt_i32_f32_e32 v164, v164
	v_cvt_i32_f32_e32 v165, v165
	v_cvt_i32_f32_e32 v166, v166
	v_cvt_i32_f32_e32 v167, v167
	v_and_b32_e32 v164, 0xff, v164
	v_and_b32_e32 v165, 0xff, v165
	v_and_b32_e32 v166, 0xff, v166
	v_lshl_or_b32 v164, v165, 8, v164
	v_lshl_or_b32 v164, v166, 16, v164
	v_lshl_or_b32 v222, v167, 24, v164
	v_pk_mul_f32 v[224:225], v[18:19], v[18:19]
	v_pk_mul_f32 v[226:227], v[20:21], v[20:21]
	v_pk_add_f32 v[14:15], v[14:15], v[206:207]
	v_pk_add_f32 v[16:17], v[16:17], v[208:209]
	v_cvt_pk_bf16_f32 v220, v14, v15
	v_cvt_pk_bf16_f32 v221, v16, v17
	v_mul_f32_e32 v164, v228, v14
	v_mul_f32_e32 v165, v228, v15
	v_mul_f32_e32 v166, v228, v16
	v_mul_f32_e32 v167, v228, v17
	v_rndne_f32_e32 v164, v164
	v_rndne_f32_e32 v165, v165
	v_rndne_f32_e32 v166, v166
	v_rndne_f32_e32 v167, v167
	v_med3_f32 v164, v164, s71, v183
	v_med3_f32 v165, v165, s71, v183
	v_med3_f32 v166, v166, s71, v183
	v_med3_f32 v167, v167, s71, v183
	v_cvt_i32_f32_e32 v164, v164
	v_cvt_i32_f32_e32 v165, v165
	v_cvt_i32_f32_e32 v166, v166
	v_cvt_i32_f32_e32 v167, v167
	v_and_b32_e32 v164, 0xff, v164
	v_and_b32_e32 v165, 0xff, v165
	v_and_b32_e32 v166, 0xff, v166
	v_lshl_or_b32 v164, v165, 8, v164
	v_lshl_or_b32 v164, v166, 16, v164
	v_lshl_or_b32 v223, v167, 24, v164
	v_pk_fma_f32 v[224:225], v[14:15], v[14:15], v[224:225]
	v_pk_fma_f32 v[226:227], v[16:17], v[16:17], v[226:227]
	global_store_dwordx4 v136, v[218:221], s[86:87]
	global_store_dwordx2 v137, v[222:223], s[88:89]
	s_nop 0
	v_pk_add_f32 v[10:11], v[10:11], v[210:211]
	v_pk_add_f32 v[12:13], v[12:13], v[212:213]
	v_cvt_pk_bf16_f32 v218, v10, v11
	v_cvt_pk_bf16_f32 v219, v12, v13
	v_mul_f32_e32 v164, v228, v10
	v_mul_f32_e32 v165, v228, v11
	v_mul_f32_e32 v166, v228, v12
	v_mul_f32_e32 v167, v228, v13
	v_rndne_f32_e32 v164, v164
	v_rndne_f32_e32 v165, v165
	v_rndne_f32_e32 v166, v166
	v_rndne_f32_e32 v167, v167
	v_med3_f32 v164, v164, s71, v183
	v_med3_f32 v165, v165, s71, v183
	v_med3_f32 v166, v166, s71, v183
	v_med3_f32 v167, v167, s71, v183
	v_cvt_i32_f32_e32 v164, v164
	v_cvt_i32_f32_e32 v165, v165
	v_cvt_i32_f32_e32 v166, v166
	v_cvt_i32_f32_e32 v167, v167
	v_and_b32_e32 v164, 0xff, v164
	v_and_b32_e32 v165, 0xff, v165
	v_and_b32_e32 v166, 0xff, v166
	v_lshl_or_b32 v164, v165, 8, v164
	v_lshl_or_b32 v164, v166, 16, v164
	v_lshl_or_b32 v222, v167, 24, v164
	v_pk_fma_f32 v[224:225], v[10:11], v[10:11], v[224:225]
	v_pk_fma_f32 v[226:227], v[12:13], v[12:13], v[226:227]
	v_pk_add_f32 v[6:7], v[6:7], v[214:215]
	v_pk_add_f32 v[8:9], v[8:9], v[216:217]
	v_cvt_pk_bf16_f32 v220, v6, v7
	v_cvt_pk_bf16_f32 v221, v8, v9
	v_mul_f32_e32 v164, v228, v6
	v_mul_f32_e32 v165, v228, v7
	v_mul_f32_e32 v166, v228, v8
	v_mul_f32_e32 v167, v228, v9
	v_rndne_f32_e32 v164, v164
	v_rndne_f32_e32 v165, v165
	v_rndne_f32_e32 v166, v166
	v_rndne_f32_e32 v167, v167
	v_med3_f32 v164, v164, s71, v183
	v_med3_f32 v165, v165, s71, v183
	v_med3_f32 v166, v166, s71, v183
	v_med3_f32 v167, v167, s71, v183
	v_cvt_i32_f32_e32 v164, v164
	v_cvt_i32_f32_e32 v165, v165
	v_cvt_i32_f32_e32 v166, v166
	v_cvt_i32_f32_e32 v167, v167
	v_and_b32_e32 v164, 0xff, v164
	v_and_b32_e32 v165, 0xff, v165
	v_and_b32_e32 v166, 0xff, v166
	v_lshl_or_b32 v164, v165, 8, v164
	v_lshl_or_b32 v164, v166, 16, v164
	v_lshl_or_b32 v223, v167, 24, v164
	v_pk_fma_f32 v[224:225], v[6:7], v[6:7], v[224:225]
	v_pk_fma_f32 v[226:227], v[8:9], v[8:9], v[226:227]
	global_store_dwordx4 v136, v[218:221], s[86:87] offset:256
	global_store_dwordx2 v137, v[222:223], s[88:89] offset:128
	s_nop 0
	v_add_f32_e32 v224, v224, v225
	v_add_f32_e32 v226, v226, v227
	v_add_f32_e32 v224, v224, v226
	ds_bpermute_b32 v225, v138, v224
	s_waitcnt lgkmcnt(0)
	v_add_f32_e32 v224, v224, v225
	ds_bpermute_b32 v225, v139, v224
	s_waitcnt lgkmcnt(0)
	v_add_f32_e32 v224, v224, v225
	s_and_saveexec_b64 s[32:33], s[6:7]
	global_atomic_add_f32 v134, v224, s[16:17] offset:704
	s_or_b64 exec, exec, s[32:33]
	s_nop 1
	s_andn2_b64 vcc, exec, s[8:9]
	s_mov_b64 s[8:9], -1
	s_cbranch_vccnz .LBB0_1124
	s_andn2_b64 vcc, exec, s[24:25]
	s_cbranch_vccnz .LBB0_1123
	s_barrier
	s_branch .LBB0_1123
